# mlstm2: next chunk's K/Q rows touched during the state update (L2 warm-up loads, results discarded)
# baseline (speedup 1.0000x reference)
; __device__ __forceinline__ u16 f2bf(float f) { return (u16)(pk2(f, 0.f) & 0xffffu); }
; #define MFMA16(a, b, c) __builtin_amdgcn_mfma_f32_16x16x32_bf16((a), (b), (c), 0, 0, 0)
; __device__ void mlstm2_phase(const Params& p, unsigned char* smem) {
;     ...
; #pragma unroll
;             for (int ks = 0; ks < 8; ++ks)
; #pragma unroll
;                 for (int nt = 0; nt < 3; ++nt) { const bf16x8 cf = *(const bf16x8*)(Ct + (16 * nt + l15) * 264 + 32 * ks + 8 * lq); oc[nt] = MFMA16(qf[ks], cf, oc[nt]); }
; #pragma unroll
;             for (int r = 0; r < 4; ++r) { const int t = 16 * wave + 4 * lq + r; const float Rf = gR[t], E = gE[t], F = gF[t];
;                 float den = Rf * oi[2][r] + E * oc[2][r]; den = __shfl(den, lane & 48);
;                 const float inv = 1.0f / fmaxf(fabsf(den), F);
; #pragma unroll
;                 for (int nt = 0; nt < 2; ++nt) Hm[(size_t)(row0 + t) * 2048 + 256 * h + 32 * sl + 16 * nt + l15] = f2bf((Rf * oi[nt][r] + E * oc[nt][r]) * inv); }
.LBB0_422:
	v_add_u32_e32 v82, v124, v150
	ds_read_b128 v[70:73], v82
	ds_read_b128 v[74:77], v219
	ds_read_b128 v[78:81], v219 offset:8448
	s_waitcnt lgkmcnt(2)
	v_mfma_f32_16x16x32_bf16 v[70:73], v[54:57], v[70:73], 0
	s_waitcnt lgkmcnt(1)
	v_mfma_f32_16x16x32_bf16 v[74:77], v[54:57], v[74:77], 0
	s_waitcnt lgkmcnt(0)
	v_mfma_f32_16x16x32_bf16 v[54:57], v[54:57], v[78:81], 0
	ds_read_b128 v[78:81], v82 offset:64
	s_waitcnt lgkmcnt(0)
	v_mfma_f32_16x16x32_bf16 v[70:73], v[50:53], v[78:81], v[70:73]
	ds_read_b128 v[78:81], v219 offset:64
	s_waitcnt lgkmcnt(0)
	v_mfma_f32_16x16x32_bf16 v[74:77], v[50:53], v[78:81], v[74:77]
	ds_read_b128 v[78:81], v219 offset:8512
	s_waitcnt lgkmcnt(0)
	v_mfma_f32_16x16x32_bf16 v[50:53], v[50:53], v[78:81], v[54:57]
	s_nop 2
	ds_read_b128 v[54:57], v82 offset:128
	s_waitcnt lgkmcnt(0)
	v_mfma_f32_16x16x32_bf16 v[54:57], v[46:49], v[54:57], v[70:73]
	s_nop 2
	ds_read_b128 v[70:73], v219 offset:128
	s_waitcnt lgkmcnt(0)
	v_mfma_f32_16x16x32_bf16 v[70:73], v[46:49], v[70:73], v[74:77]
	s_nop 2
	ds_read_b128 v[74:77], v219 offset:8576
	s_waitcnt lgkmcnt(0)
	v_mfma_f32_16x16x32_bf16 v[46:49], v[46:49], v[74:77], v[50:53]
	s_nop 2
	ds_read_b128 v[50:53], v82 offset:192
	s_waitcnt lgkmcnt(0)
	v_mfma_f32_16x16x32_bf16 v[50:53], v[42:45], v[50:53], v[54:57]
	s_nop 2
	ds_read_b128 v[54:57], v219 offset:192
	s_waitcnt lgkmcnt(0)
	v_mfma_f32_16x16x32_bf16 v[54:57], v[42:45], v[54:57], v[70:73]
	s_nop 2
	ds_read_b128 v[70:73], v219 offset:8640
	s_waitcnt lgkmcnt(0)
	v_mfma_f32_16x16x32_bf16 v[42:45], v[42:45], v[70:73], v[46:49]
	s_nop 2
	ds_read_b128 v[46:49], v82 offset:256
	s_waitcnt lgkmcnt(0)
	v_mfma_f32_16x16x32_bf16 v[46:49], v[38:41], v[46:49], v[50:53]
	s_nop 2
	ds_read_b128 v[50:53], v219 offset:256
	s_waitcnt lgkmcnt(0)
	v_mfma_f32_16x16x32_bf16 v[50:53], v[38:41], v[50:53], v[54:57]
	s_nop 2
	ds_read_b128 v[54:57], v219 offset:8704
	s_waitcnt lgkmcnt(0)
	v_mfma_f32_16x16x32_bf16 v[38:41], v[38:41], v[54:57], v[42:45]
	s_nop 2
	ds_read_b128 v[42:45], v82 offset:320
	s_waitcnt lgkmcnt(0)
	v_mfma_f32_16x16x32_bf16 v[42:45], v[34:37], v[42:45], v[46:49]
	s_nop 2
	ds_read_b128 v[46:49], v219 offset:320
	s_waitcnt lgkmcnt(0)
	v_mfma_f32_16x16x32_bf16 v[46:49], v[34:37], v[46:49], v[50:53]
	s_nop 2
	ds_read_b128 v[50:53], v219 offset:8768
	s_waitcnt lgkmcnt(0)
	v_mfma_f32_16x16x32_bf16 v[34:37], v[34:37], v[50:53], v[38:41]
	s_nop 2
	ds_read_b128 v[38:41], v82 offset:384
	s_waitcnt lgkmcnt(0)
	v_mfma_f32_16x16x32_bf16 v[38:41], v[30:33], v[38:41], v[42:45]
	s_nop 2
	ds_read_b128 v[42:45], v219 offset:384
	s_waitcnt lgkmcnt(0)
	v_mfma_f32_16x16x32_bf16 v[42:45], v[30:33], v[42:45], v[46:49]
	s_nop 2
	ds_read_b128 v[46:49], v219 offset:8832
	s_waitcnt lgkmcnt(0)
	v_mfma_f32_16x16x32_bf16 v[46:49], v[30:33], v[46:49], v[34:37]
	ds_read_b128 v[30:33], v82 offset:448
	s_waitcnt lgkmcnt(0)
	v_mfma_f32_16x16x32_bf16 v[34:37], v[26:29], v[30:33], v[38:41]
	ds_read_b128 v[30:33], v219 offset:448
	s_nop 1
	ds_read_b128 v[38:41], v219 offset:8896
	s_waitcnt lgkmcnt(1)
	v_mfma_f32_16x16x32_bf16 v[30:33], v[26:29], v[30:33], v[42:45]
	s_waitcnt lgkmcnt(0)
	v_mfma_f32_16x16x32_bf16 v[26:29], v[26:29], v[38:41], v[46:49]
	ds_read_b32 v39, v197
	ds_read_b32 v44, v198
	ds_read_b32 v40, v199
	v_and_or_b32 v38, v226, 64, v121
	v_lshlrev_b32_e32 v38, 2, v38
	s_waitcnt lgkmcnt(1)
	s_nop 1
	v_mul_f32_e32 v26, v26, v44
	v_fmac_f32_e32 v26, v66, v39
	ds_bpermute_b32 v26, v38, v26
	s_waitcnt lgkmcnt(1)
	v_max_f32_e32 v40, v40, v40
	v_mul_f32_e32 v34, v34, v44
	v_mul_f32_e32 v30, v30, v44
	v_fmac_f32_e32 v34, v62, v39
	s_waitcnt lgkmcnt(0)
	v_max_f32_e64 v26, |v26|, |v26|
	v_max_f32_e32 v26, v26, v40
	v_div_scale_f32 v40, s[26:27], v26, v26, 1.0
	v_rcp_f32_e32 v41, v40
	v_fmac_f32_e32 v30, v58, v39
	v_fma_f32 v42, -v40, v41, 1.0
	v_fmac_f32_e32 v41, v42, v41
	v_div_scale_f32 v42, vcc, 1.0, v26, 1.0
	v_mul_f32_e32 v43, v42, v41
	v_fma_f32 v45, -v40, v43, v42
	v_fmac_f32_e32 v43, v45, v41
	v_fma_f32 v40, -v40, v43, v42
	v_div_fmas_f32 v40, v40, v41, v43
	v_div_fixup_f32 v26, v40, v26, 1.0
	v_add_u32_e32 v40, s79, v230
	v_ashrrev_i32_e32 v41, 31, v40
	v_lshlrev_b64 v[42:43], 12, v[40:41]
	v_lshl_add_u64 v[42:43], v[108:109], 0, v[42:43]
	v_mul_f32_e32 v34, v34, v26
	v_mul_f32_e32 v26, v30, v26
	v_cvt_pk_bf16_f32 v34, v34, v93
	global_store_short v[42:43], v34, off
	v_cvt_pk_bf16_f32 v26, v26, v93
	global_store_short v[42:43], v26, off offset:32
	ds_read_b32 v30, v200
	ds_read_b32 v34, v201
	ds_read_b32 v26, v202
	s_addk_i32 s79, 0x80
	s_cmpk_eq_i32 s79, 0x1000
	s_waitcnt lgkmcnt(1)
	v_mul_f32_e32 v27, v27, v34
	v_fmac_f32_e32 v27, v67, v30
	ds_bpermute_b32 v27, v38, v27
	s_waitcnt lgkmcnt(1)
	v_max_f32_e32 v26, v26, v26
	v_mul_f32_e32 v35, v35, v34
	v_mul_f32_e32 v31, v31, v34
	v_fmac_f32_e32 v35, v63, v30
	s_waitcnt lgkmcnt(0)
	v_max_f32_e64 v27, |v27|, |v27|
	v_max_f32_e32 v26, v27, v26
	v_div_scale_f32 v27, s[26:27], v26, v26, 1.0
	v_rcp_f32_e32 v39, v27
	v_fmac_f32_e32 v31, v59, v30
	v_fma_f32 v41, -v27, v39, 1.0
	v_fmac_f32_e32 v39, v41, v39
	v_div_scale_f32 v41, vcc, 1.0, v26, 1.0
	v_mul_f32_e32 v42, v41, v39
	v_fma_f32 v43, -v27, v42, v41
	v_fmac_f32_e32 v42, v43, v39
	v_fma_f32 v27, -v27, v42, v41
	v_div_fmas_f32 v27, v27, v39, v42
	v_div_fixup_f32 v39, v27, v26, 1.0
	v_add_u32_e32 v26, 1, v40
	v_ashrrev_i32_e32 v27, 31, v26
	v_lshlrev_b64 v[26:27], 12, v[26:27]
	v_lshl_add_u64 v[26:27], v[108:109], 0, v[26:27]
	v_mul_f32_e32 v35, v35, v39
	v_mul_f32_e32 v30, v31, v39
	v_cvt_pk_bf16_f32 v35, v35, v93
	global_store_short v[26:27], v35, off
	v_cvt_pk_bf16_f32 v30, v30, v93
	global_store_short v[26:27], v30, off offset:32
	ds_read_b32 v30, v203
	ds_read_b32 v31, v204
	ds_read_b32 v26, v205
	s_waitcnt lgkmcnt(1)
; __device__ __forceinline__ u16 f2bf(float f) { return (u16)(pk2(f, 0.f) & 0xffffu); }
; __device__ void mlstm2_phase(const Params& p, unsigned char* smem) {
;     ...
;             for (int r = 0; r < 4; ++r) { const int t = 16 * wave + 4 * lq + r; const float Rf = gR[t], E = gE[t], F = gF[t];
;                 float den = Rf * oi[2][r] + E * oc[2][r]; den = __shfl(den, lane & 48);
;                 const float inv = 1.0f / fmaxf(fabsf(den), F);
; #pragma unroll
;                 for (int nt = 0; nt < 2; ++nt) Hm[(size_t)(row0 + t) * 2048 + 256 * h + 32 * sl + 16 * nt + l15] = f2bf((Rf * oi[nt][r] + E * oc[nt][r]) * inv); }
;             { const float decay = gS[0];
; #pragma unroll
;               for (int a = 0; a < 3; ++a)
; #pragma unroll
;                 for (int c = 0; c < 2; ++c) accC[a][c] = accC[a][c] * decay; }
; #pragma unroll
;             for (int kk = 0; kk < 4; ++kk) {
;                 bf16x8 ktf[2];
; #pragma unroll
;                 for (int ntk = 0; ntk < 2; ++ntk) { const int dk = 32 * wave + 16 * ntk + l15;
; #pragma unroll
;                     for (int j = 0; j < 8; ++j) ktf[ntk][j] = (short)Ks[(32 * kk + 8 * lq + j) * 264 + dk]; }
	v_mul_f32_e32 v27, v28, v31
	v_fmac_f32_e32 v27, v68, v30
	ds_bpermute_b32 v27, v38, v27
	s_waitcnt lgkmcnt(1)
	v_max_f32_e32 v26, v26, v26
	s_waitcnt lgkmcnt(0)
	v_max_f32_e64 v27, |v27|, |v27|
	v_max_f32_e32 v26, v27, v26
	v_div_scale_f32 v27, s[26:27], v26, v26, 1.0
	v_rcp_f32_e32 v28, v27
	s_nop 0
	v_fma_f32 v34, -v27, v28, 1.0
	v_fmac_f32_e32 v28, v34, v28
	v_div_scale_f32 v34, vcc, 1.0, v26, 1.0
	v_mul_f32_e32 v35, v34, v28
	v_fma_f32 v39, -v27, v35, v34
	v_fmac_f32_e32 v35, v39, v28
	v_fma_f32 v27, -v27, v35, v34
	v_div_fmas_f32 v27, v27, v28, v35
	v_div_fixup_f32 v28, v27, v26, 1.0
	v_add_u32_e32 v26, 2, v40
	v_ashrrev_i32_e32 v27, 31, v26
	v_mul_f32_e32 v34, v36, v31
	v_mul_f32_e32 v31, v32, v31
	v_lshlrev_b64 v[26:27], 12, v[26:27]
	v_fmac_f32_e32 v34, v64, v30
	v_fmac_f32_e32 v31, v60, v30
	v_lshl_add_u64 v[26:27], v[108:109], 0, v[26:27]
	v_mul_f32_e32 v34, v34, v28
	v_mul_f32_e32 v28, v31, v28
	v_cvt_pk_bf16_f32 v34, v34, v93
	global_store_short v[26:27], v34, off
	v_cvt_pk_bf16_f32 v28, v28, v93
	global_store_short v[26:27], v28, off offset:32
	ds_read_b32 v28, v206
	ds_read_b32 v30, v207
	ds_read_b32 v26, v208
	s_waitcnt lgkmcnt(1)
	v_mul_f32_e32 v27, v29, v30
	v_fmac_f32_e32 v27, v69, v28
	ds_bpermute_b32 v27, v38, v27
	s_waitcnt lgkmcnt(1)
	v_max_f32_e32 v26, v26, v26
	s_waitcnt lgkmcnt(0)
	v_max_f32_e64 v27, |v27|, |v27|
	v_max_f32_e32 v26, v27, v26
	v_div_scale_f32 v27, s[26:27], v26, v26, 1.0
	v_rcp_f32_e32 v29, v27
	s_nop 0
	v_fma_f32 v31, -v27, v29, 1.0
	v_fmac_f32_e32 v29, v31, v29
	v_div_scale_f32 v31, vcc, 1.0, v26, 1.0
	v_mul_f32_e32 v32, v31, v29
	v_fma_f32 v34, -v27, v32, v31
	v_fmac_f32_e32 v32, v34, v29
	v_fma_f32 v27, -v27, v32, v31
	v_div_fmas_f32 v27, v27, v29, v32
	v_div_fixup_f32 v29, v27, v26, 1.0
	v_add_u32_e32 v26, 3, v40
	v_ashrrev_i32_e32 v27, 31, v26
	v_mul_f32_e32 v31, v37, v30
	v_mul_f32_e32 v30, v33, v30
	v_lshlrev_b64 v[26:27], 12, v[26:27]
	v_fmac_f32_e32 v31, v65, v28
	v_fmac_f32_e32 v30, v61, v28
	v_lshl_add_u64 v[26:27], v[108:109], 0, v[26:27]
	v_mul_f32_e32 v31, v31, v29
	v_mul_f32_e32 v28, v30, v29
	v_cvt_pk_bf16_f32 v31, v31, v93
	global_store_short v[26:27], v31, off
	v_cvt_pk_bf16_f32 v28, v28, v93
	global_store_short v[26:27], v28, off offset:32
	v_mov_b32_e32 v26, s91
	ds_read_b32 v34, v26
	v_and_b32_e32 v27, 15, v0
	v_lshrrev_b32_e32 v28, 2, v27
	v_and_b32_e32 v29, 3, v27
	v_lshlrev_b32_e32 v27, 1, v27
	v_sub_u32_e32 v27, v209, v27
	v_mul_u32_u24_e32 v28, 0x210, v28
	v_lshl_add_u32 v27, v29, 3, v27
	v_add_u32_e32 v27, v27, v28
	ds_read_b64_tr_b16 v[36:37], v27
	ds_read_b64_tr_b16 v[38:39], v27 offset:2112
	ds_read_b64_tr_b16 v[40:41], v27 offset:32
	ds_read_b64_tr_b16 v[42:43], v27 offset:2144
	ds_read_b128 v[44:47], v220
	ds_read_b128 v[48:51], v220 offset:4352
	ds_read_b128 v[52:55], v220 offset:8704
	ds_read_b64_tr_b16 v[56:57], v27 offset:16896
	ds_read_b64_tr_b16 v[58:59], v27 offset:19008
	ds_read_b64_tr_b16 v[60:61], v27 offset:16928
	ds_read_b64_tr_b16 v[62:63], v27 offset:19040
	ds_read_b128 v[64:67], v220 offset:64
	ds_read_b128 v[68:71], v220 offset:4416
	ds_read_b128 v[72:75], v220 offset:8768
	v_add_u32_e32 v98, s79, v235
	v_ashrrev_i32_e32 v99, 31, v98
	v_lshlrev_b64 v[98:99], 12, v[98:99]
	v_lshl_add_u64 v[98:99], v[102:103], 0, v[98:99]
	global_load_dword v218, v[98:99], off
	v_add_u32_e32 v98, s79, v238
	v_ashrrev_i32_e32 v99, 31, v98
	v_lshlrev_b64 v[98:99], 12, v[98:99]
	v_lshl_add_u64 v[98:99], v[102:103], 0, v[98:99]
	global_load_dword v218, v[98:99], off
	v_add_u32_e32 v98, s79, v235
	v_add_u32_e32 v98, 32, v98
	v_ashrrev_i32_e32 v99, 31, v98
	v_lshlrev_b64 v[98:99], 12, v[98:99]
	v_lshl_add_u64 v[98:99], v[102:103], 0, v[98:99]
	global_load_dword v218, v[98:99], off
	v_add_u32_e32 v98, s79, v237
	v_ashrrev_i32_e32 v99, 31, v98
	v_lshlrev_b64 v[98:99], 12, v[98:99]
	v_lshl_add_u64 v[98:99], v[102:103], 0, v[98:99]
	global_load_dword v218, v[98:99], off
	v_add_u32_e32 v98, s79, v235
	v_add_u32_e32 v98, 64, v98
	v_ashrrev_i32_e32 v99, 31, v98
	v_lshlrev_b64 v[98:99], 12, v[98:99]
	v_lshl_add_u64 v[98:99], v[102:103], 0, v[98:99]
	global_load_dword v218, v[98:99], off
	v_add_u32_e32 v98, s79, v236
	v_ashrrev_i32_e32 v99, 31, v98
	v_lshlrev_b64 v[98:99], 12, v[98:99]
	v_lshl_add_u64 v[98:99], v[102:103], 0, v[98:99]
	global_load_dword v218, v[98:99], off
	v_add_u32_e32 v98, s79, v235
	v_add_u32_e32 v98, 96, v98
	v_ashrrev_i32_e32 v99, 31, v98
	v_lshlrev_b64 v[98:99], 12, v[98:99]
	v_lshl_add_u64 v[98:99], v[102:103], 0, v[98:99]
	global_load_dword v218, v[98:99], off
	v_add_u32_e32 v98, s79, v234
	v_ashrrev_i32_e32 v99, 31, v98
	v_lshlrev_b64 v[98:99], 12, v[98:99]
	v_lshl_add_u64 v[98:99], v[102:103], 0, v[98:99]
	global_load_dword v218, v[98:99], off
	v_add_u32_e32 v98, s79, v233
	v_ashrrev_i32_e32 v99, 31, v98
	v_lshlrev_b64 v[98:99], 12, v[98:99]
	v_lshl_add_u64 v[98:99], v[104:105], 0, v[98:99]
	global_load_dword v218, v[98:99], off
	global_load_dword v218, v[98:99], off offset:64
	global_load_dword v218, v[98:99], off offset:128
	global_load_dword v218, v[98:99], off offset:192
	global_load_dword v218, v[98:99], off offset:256
	global_load_dword v218, v[98:99], off offset:320
	global_load_dword v218, v[98:99], off offset:384
	global_load_dword v218, v[98:99], off offset:448
	s_waitcnt lgkmcnt(14)
; __device__ __forceinline__ u16 f2bf(float f) { return (u16)(pk2(f, 0.f) & 0xffffu); }
; #define MFMA16(a, b, c) __builtin_amdgcn_mfma_f32_16x16x32_bf16((a), (b), (c), 0, 0, 0)
; __device__ void mlstm2_phase(const Params& p, unsigned char* smem) {
;     ...
;             { const float decay = gS[0];
; #pragma unroll
;               for (int a = 0; a < 3; ++a)
; #pragma unroll
;                 for (int c = 0; c < 2; ++c) accC[a][c] = accC[a][c] * decay; }
; #pragma unroll
;             for (int kk = 0; kk < 4; ++kk) {
;                 bf16x8 ktf[2];
; #pragma unroll
;                 for (int ntk = 0; ntk < 2; ++ntk) { const int dk = 32 * wave + 16 * ntk + l15;
; #pragma unroll
;                     for (int j = 0; j < 8; ++j) ktf[ntk][j] = (short)Ks[(32 * kk + 8 * lq + j) * 264 + dk]; }
; #pragma unroll
;                 for (int mt = 0; mt < 3; ++mt) { const bf16x8 vwf = *(const bf16x8*)(Vwt + (16 * mt + l15) * 136 + 32 * kk + 8 * lq);
; #pragma unroll
;                     for (int ntk = 0; ntk < 2; ++ntk) accC[mt][ntk] = MFMA16(vwf, ktf[ntk], accC[mt][ntk]); }
;             }
;             __syncthreads();
; #pragma unroll
;             for (int mt = 0; mt < 3; ++mt)
; #pragma unroll
;                 for (int ntk = 0; ntk < 2; ++ntk)
; #pragma unroll
;                     for (int r = 0; r < 4; ++r) Ct[(16 * mt + 4 * lq + r) * 264 + 32 * wave + 16 * ntk + l15] = f2bf(accC[mt][ntk][r]);
	v_pk_mul_f32 v[2:3], v[2:3], v[34:35] op_sel_hi:[1,0]
	v_pk_mul_f32 v[4:5], v[4:5], v[34:35] op_sel_hi:[1,0]
	v_pk_mul_f32 v[6:7], v[6:7], v[34:35] op_sel_hi:[1,0]
	v_pk_mul_f32 v[8:9], v[8:9], v[34:35] op_sel_hi:[1,0]
	v_pk_mul_f32 v[10:11], v[10:11], v[34:35] op_sel_hi:[1,0]
	v_pk_mul_f32 v[12:13], v[12:13], v[34:35] op_sel_hi:[1,0]
	v_pk_mul_f32 v[14:15], v[14:15], v[34:35] op_sel_hi:[1,0]
	v_pk_mul_f32 v[16:17], v[16:17], v[34:35] op_sel_hi:[1,0]
	v_pk_mul_f32 v[18:19], v[18:19], v[34:35] op_sel_hi:[1,0]
	v_pk_mul_f32 v[20:21], v[20:21], v[34:35] op_sel_hi:[1,0]
	v_pk_mul_f32 v[22:23], v[22:23], v[34:35] op_sel_hi:[1,0]
	v_pk_mul_f32 v[24:25], v[24:25], v[34:35] op_sel_hi:[1,0]
	s_waitcnt lgkmcnt(7)
	v_mfma_f32_16x16x32_bf16 v[2:5], v[44:47], v[36:39], v[2:5]
	v_mfma_f32_16x16x32_bf16 v[6:9], v[44:47], v[40:43], v[6:9]
	v_mfma_f32_16x16x32_bf16 v[10:13], v[48:51], v[36:39], v[10:13]
	v_mfma_f32_16x16x32_bf16 v[14:17], v[48:51], v[40:43], v[14:17]
	v_mfma_f32_16x16x32_bf16 v[18:21], v[52:55], v[36:39], v[18:21]
	v_mfma_f32_16x16x32_bf16 v[22:25], v[52:55], v[40:43], v[22:25]
	ds_read_b64_tr_b16 v[36:37], v27 offset:33792
	ds_read_b64_tr_b16 v[38:39], v27 offset:35904
	ds_read_b64_tr_b16 v[40:41], v27 offset:33824
	ds_read_b64_tr_b16 v[42:43], v27 offset:35936
	ds_read_b128 v[44:47], v220 offset:128
	ds_read_b128 v[48:51], v220 offset:4480
	ds_read_b128 v[52:55], v220 offset:8832
	s_waitcnt lgkmcnt(7)
	v_mfma_f32_16x16x32_bf16 v[2:5], v[64:67], v[56:59], v[2:5]
	v_mfma_f32_16x16x32_bf16 v[6:9], v[64:67], v[60:63], v[6:9]
	v_mfma_f32_16x16x32_bf16 v[10:13], v[68:71], v[56:59], v[10:13]
	v_mfma_f32_16x16x32_bf16 v[14:17], v[68:71], v[60:63], v[14:17]
	v_mfma_f32_16x16x32_bf16 v[18:21], v[72:75], v[56:59], v[18:21]
	v_mfma_f32_16x16x32_bf16 v[22:25], v[72:75], v[60:63], v[22:25]
	ds_read_b64_tr_b16 v[56:57], v27 offset:50688
	ds_read_b64_tr_b16 v[58:59], v27 offset:52800
	ds_read_b64_tr_b16 v[60:61], v27 offset:50720
	ds_read_b64_tr_b16 v[62:63], v27 offset:52832
	ds_read_b128 v[64:67], v220 offset:192
	ds_read_b128 v[68:71], v220 offset:4544
	ds_read_b128 v[72:75], v220 offset:8896
	s_waitcnt lgkmcnt(7)
	v_mfma_f32_16x16x32_bf16 v[2:5], v[44:47], v[36:39], v[2:5]
	v_mfma_f32_16x16x32_bf16 v[6:9], v[44:47], v[40:43], v[6:9]
	v_mfma_f32_16x16x32_bf16 v[10:13], v[48:51], v[36:39], v[10:13]
	v_mfma_f32_16x16x32_bf16 v[14:17], v[48:51], v[40:43], v[14:17]
	v_mfma_f32_16x16x32_bf16 v[18:21], v[52:55], v[36:39], v[18:21]
	v_mfma_f32_16x16x32_bf16 v[22:25], v[52:55], v[40:43], v[22:25]
	s_waitcnt lgkmcnt(0)
	v_mfma_f32_16x16x32_bf16 v[2:5], v[64:67], v[56:59], v[2:5]
	v_mfma_f32_16x16x32_bf16 v[6:9], v[64:67], v[60:63], v[6:9]
	v_mfma_f32_16x16x32_bf16 v[10:13], v[68:71], v[56:59], v[10:13]
	v_mfma_f32_16x16x32_bf16 v[14:17], v[68:71], v[60:63], v[14:17]
	v_mfma_f32_16x16x32_bf16 v[18:21], v[72:75], v[56:59], v[18:21]
	v_mfma_f32_16x16x32_bf16 v[22:25], v[72:75], v[60:63], v[22:25]
	s_barrier
	s_nop 7
	s_nop 3
	v_cvt_pk_bf16_f32 v26, v2, v3
	ds_write_b16 v221, v26
	ds_write_b16_d16_hi v221, v26 offset:528
	v_cvt_pk_bf16_f32 v26, v4, v5
	ds_write_b16 v221, v26 offset:1056
	ds_write_b16_d16_hi v221, v26 offset:1584
	v_cvt_pk_bf16_f32 v26, v6, v7
	ds_write_b16 v221, v26 offset:32
	ds_write_b16_d16_hi v221, v26 offset:560
	v_cvt_pk_bf16_f32 v26, v8, v9
	ds_write_b16 v221, v26 offset:1088
	ds_write_b16_d16_hi v221, v26 offset:1616
	v_cvt_pk_bf16_f32 v26, v10, v11
	ds_write_b16 v221, v26 offset:8448
	ds_write_b16_d16_hi v221, v26 offset:8976
	v_cvt_pk_bf16_f32 v26, v12, v13
	ds_write_b16 v221, v26 offset:9504
	ds_write_b16_d16_hi v221, v26 offset:10032
	v_cvt_pk_bf16_f32 v26, v14, v15
	ds_write_b16 v221, v26 offset:8480
	ds_write_b16_d16_hi v221, v26 offset:9008
	v_cvt_pk_bf16_f32 v26, v16, v17
	ds_write_b16 v221, v26 offset:9536
	ds_write_b16_d16_hi v221, v26 offset:10064
	v_cvt_pk_bf16_f32 v26, v18, v19
	ds_write_b16 v221, v26 offset:16896
	ds_write_b16_d16_hi v221, v26 offset:17424
	v_cvt_pk_bf16_f32 v26, v20, v21
	ds_write_b16 v221, v26 offset:17952
	ds_write_b16_d16_hi v221, v26 offset:18480
	v_cvt_pk_bf16_f32 v26, v22, v23
	ds_write_b16 v221, v26 offset:16928
	ds_write_b16_d16_hi v221, v26 offset:17456
	v_cvt_pk_bf16_f32 v26, v24, v25
	ds_write_b16 v221, v26 offset:17984
	ds_write_b16_d16_hi v221, v26 offset:18512
	s_cbranch_scc1 .LBB0_414
